# FF2 layer-1 epilogue de-serialised: the second column-half's residual and gate loads are issued with the first half's (before any store) into free registers, one wait per half
# speedup vs baseline: 1.0193x; 1.0193x over previous
;     __device__ __forceinline__ void operator()(const f32x4 (&acc)[2][2][4][2], const Unit& u, int wr, int wc, int fr, int fq) const {
;     ...
;         for (int bj = 0; bj < 2; ++bj) { const int cb = c0 + bj * HALF;
;             const f32x4 g0 = ldb<f32x4>(gate, (unsigned)((b * NMOD + cb) * 4)), g1 = ldb<f32x4>(gate, (unsigned)((b * NMOD + cb + 4) * 4));
;             f32x4 m0 = (f32x4){0.f, 0.f, 0.f, 0.f}, m1 = m0; if (gm) { m0 = ldb<f32x4>(gm, (unsigned)((b * DM + cb) * 4)); m1 = ldb<f32x4>(gm, (unsigned)((b * DM + cb + 4) * 4)); }
;             if (XF32) {
; #pragma unroll
;                 for (int ai = 0; ai < 2; ++ai) {
;                     f32x4 xv[4][2];
; #pragma unroll
;                     for (int m = 0; m < 4; ++m) { const unsigned off = (unsigned)((PG8_ROW(u, ai, m) * DM + cb) * 4); xv[m][0] = ldb<f32x4>(xin, off); xv[m][1] = ldb<f32x4>(xin, off + 16); }
;                     PG8_FENCE();
; #pragma unroll
;                     for (int m = 0; m < 4; ++m) { const unsigned off = (unsigned)((PG8_ROW(u, ai, m) * DM + cb) * 2), offx = (unsigned)(PG8_ROW(u, ai, m) * (DM * 4) + DM * 2 + cb * 2);
;                         const f32x4 x0 = xv[m][0] + g0 * (acc[ai][bj][m][0] * rs[ai][m]), x1 = xv[m][1] + g1 * (acc[ai][bj][m][1] * rs[ai][m]);
;                         stb(xout, offx, pack8(x0, x1));
;                         if (gm) { ss[ai][m] += hsq4(x0) + hsq4(x1); stb(A, off, pack8(x0 * m0, x1 * m1)); } }
;                     PG8_FENCE(); }
;             } else {
;                 u32x4 xw[2][4];
; #pragma unroll
;                 for (int ai = 0; ai < 2; ++ai)
; #pragma unroll
;                     for (int m = 0; m < 4; ++m) xw[ai][m] = ldb<u32x4>(xin, (unsigned)(PG8_ROW(u, ai, m) * (DM * 4) + DM * 2 + cb * 2));
;                 PG8_FENCE();
; #pragma unroll
;                 for (int ai = 0; ai < 2; ++ai)
; #pragma unroll
;                     for (int m = 0; m < 4; ++m) { const unsigned off = (unsigned)((PG8_ROW(u, ai, m) * DM + cb) * 2), offx = (unsigned)(PG8_ROW(u, ai, m) * (DM * 4) + DM * 2 + cb * 2);
;                         const f32x4 x0 = bf_lo4(xw[ai][m]) + g0 * (acc[ai][bj][m][0] * rs[ai][m]), x1 = bf_hi4(xw[ai][m]) + g1 * (acc[ai][bj][m][1] * rs[ai][m]);
;                         stb(xout, offx, pack8(x0, x1));
;                         if (gm) { ss[ai][m] += hsq4(x0) + hsq4(x1); stb(A, off, pack8(x0 * m0, x1 * m1)); } }
.LBB13_2166:
	v_mbcnt_lo_u32_b32 v128, -1, 0
	v_mbcnt_hi_u32_b32 v128, -1, v128
	s_lshl_b32 s11, s22, 8
	v_ashrrev_i32_e32 v129, 1, v128
	v_and_b32_e32 v129, -8, v129
	s_or_b32 s11, s11, s44
	v_add_u32_e32 v192, s11, v129
	s_lshl_b32 s11, s20, 8
	s_add_i32 s11, s11, s43
	v_and_or_b32 v128, v128, 15, s11
	v_lshlrev_b32_e32 v193, 12, v128
	v_lshl_add_u32 v136, v192, 1, v157
	v_or_b32_e32 v196, 0x20000, v193
	s_lshr_b32 s11, s20, 3
	v_add_u32_e32 v191, v136, v193
	v_or_b32_e32 v194, 0x10000, v193
	v_add_u32_e32 v197, v136, v196
	s_mulk_i32 s11, 0x1800
	v_or_b32_e32 v198, 0x30000, v193
	global_load_dwordx4 v[158:161], v191, s[6:7]
	v_add_u32_e32 v195, v136, v194
	global_load_dwordx4 v[166:169], v197, s[6:7]
	v_add_lshl_u32 v128, v192, s11, 2
	v_add_u32_e32 v199, v136, v198
	global_load_dwordx4 v[162:165], v195, s[6:7]
	global_load_dwordx4 v[170:173], v199, s[6:7]
	global_load_dwordx4 v[132:135], v128, s[4:5]
	s_nop 0
	global_load_dwordx4 v[128:131], v128, s[4:5] offset:16
	v_add_u32_e32 v200, 0x80000, v193
	v_add_u32_e32 v201, v136, v200
	global_load_dwordx4 v[174:177], v201, s[6:7]
	v_add_u32_e32 v202, 0x90000, v193
	v_add_u32_e32 v203, 0xa0000, v193
	v_add_u32_e32 v204, 0xb0000, v193
	v_add_u32_e32 v205, v136, v202
	v_add_u32_e32 v206, v136, v203
	v_add_u32_e32 v207, v136, v204
	global_load_dwordx4 v[144:147], v205, s[6:7]
	global_load_dwordx4 v[140:143], v206, s[6:7]
	global_load_dwordx4 v[136:139], v207, s[6:7]
	s_andn2_b64 vcc, exec, s[16:17]
	s_mov_b64 s[16:17], -1
	v_add_u32_e32 v210, 0x80, v192
	v_lshl_add_u32 v211, v210, 1, v157
	v_add_lshl_u32 v209, v210, s11, 2
	v_add_u32_e32 v208, v211, v193
	global_load_dwordx4 v[212:215], v208, s[6:7]
	global_load_dwordx4 v[216:219], v209, s[4:5]
	global_load_dwordx4 v[220:223], v209, s[4:5] offset:16
	v_add_u32_e32 v210, v211, v194
	global_load_dwordx4 v[224:227], v210, s[6:7]
	v_add_u32_e32 v208, v211, v196
	global_load_dwordx4 v[228:231], v208, s[6:7]
	v_add_u32_e32 v210, v211, v198
	global_load_dwordx4 v[232:235], v210, s[6:7]
	v_add_u32_e32 v208, v211, v200
	global_load_dwordx4 v[240:243], v208, s[6:7]
	v_add_u32_e32 v210, v211, v202
	global_load_dwordx4 v[244:247], v210, s[6:7]
	v_add_u32_e32 v208, v211, v203
	global_load_dwordx4 v[248:251], v208, s[6:7]
	v_add_u32_e32 v210, v211, v204
	global_load_dwordx4 v[252:255], v210, s[6:7]
	s_waitcnt vmcnt(10)
	v_lshlrev_b32_e32 v178, 16, v158
	v_and_b32_e32 v179, 0xffff0000, v158
	v_lshlrev_b32_e32 v158, 16, v159
	v_and_b32_e32 v159, 0xffff0000, v159
	v_lshlrev_b32_e32 v180, 16, v160
	v_and_b32_e32 v181, 0xffff0000, v160
	v_lshlrev_b32_e32 v160, 16, v161
	v_and_b32_e32 v161, 0xffff0000, v161
	v_lshlrev_b32_e32 v188, 16, v168
	v_and_b32_e32 v189, 0xffff0000, v168
	v_lshlrev_b32_e32 v182, 16, v162
	v_and_b32_e32 v183, 0xffff0000, v162
	v_lshlrev_b32_e32 v162, 16, v163
	v_and_b32_e32 v163, 0xffff0000, v163
	v_lshlrev_b32_e32 v168, 16, v169
	v_and_b32_e32 v169, 0xffff0000, v169
	v_pk_fma_f32 v[126:127], v[126:127], v[134:135], v[158:159]
	v_pk_fma_f32 v[124:125], v[124:125], v[132:133], v[178:179]
	v_pk_fma_f32 v[122:123], v[122:123], v[130:131], v[160:161]
	v_pk_fma_f32 v[160:161], v[104:105], v[128:129], v[188:189]
	v_cvt_pk_bf16_f32 v104, v124, v125
	v_cvt_pk_bf16_f32 v105, v126, v127
	v_lshlrev_b32_e32 v184, 16, v164
	v_and_b32_e32 v185, 0xffff0000, v164
	v_lshlrev_b32_e32 v164, 16, v165
	v_and_b32_e32 v165, 0xffff0000, v165
	v_lshlrev_b32_e32 v186, 16, v166
	v_and_b32_e32 v187, 0xffff0000, v166
	v_lshlrev_b32_e32 v166, 16, v167
	v_and_b32_e32 v167, 0xffff0000, v167
	v_pk_fma_f32 v[120:121], v[120:121], v[128:129], v[180:181]
	v_pk_fma_f32 v[118:119], v[118:119], v[134:135], v[162:163]
	v_pk_fma_f32 v[116:117], v[116:117], v[132:133], v[182:183]
	v_pk_fma_f32 v[158:159], v[106:107], v[130:131], v[168:169]
	v_cvt_pk_bf16_f32 v106, v120, v121
	v_cvt_pk_bf16_f32 v107, v122, v123
	global_store_dwordx4 v191, v[104:107], s[6:7]
	v_pk_fma_f32 v[114:115], v[114:115], v[130:131], v[164:165]
	v_pk_fma_f32 v[112:113], v[112:113], v[128:129], v[184:185]
	v_cvt_pk_bf16_f32 v104, v116, v117
	v_cvt_pk_bf16_f32 v105, v118, v119
	v_pk_fma_f32 v[110:111], v[110:111], v[134:135], v[166:167]
	v_pk_fma_f32 v[108:109], v[108:109], v[132:133], v[186:187]
	v_cvt_pk_bf16_f32 v106, v112, v113
	v_cvt_pk_bf16_f32 v107, v114, v115
	global_store_dwordx4 v195, v[104:107], s[6:7]
	v_lshlrev_b32_e32 v190, 16, v170
	v_and_b32_e32 v191, 0xffff0000, v170
	v_cvt_pk_bf16_f32 v104, v108, v109
	v_cvt_pk_bf16_f32 v105, v110, v111
	v_cvt_pk_bf16_f32 v106, v160, v161
	v_cvt_pk_bf16_f32 v107, v158, v159
	global_store_dwordx4 v197, v[104:107], s[6:7]
	v_pk_fma_f32 v[100:101], v[100:101], v[132:133], v[190:191]
	s_nop 0
	v_lshlrev_b32_e32 v104, 16, v171
	v_and_b32_e32 v105, 0xffff0000, v171
	v_pk_fma_f32 v[102:103], v[102:103], v[134:135], v[104:105]
	v_lshlrev_b32_e32 v104, 16, v172
	v_and_b32_e32 v105, 0xffff0000, v172
	v_lshlrev_b32_e32 v106, 16, v173
	v_and_b32_e32 v107, 0xffff0000, v173
	v_pk_fma_f32 v[106:107], v[98:99], v[130:131], v[106:107]
	v_pk_fma_f32 v[98:99], v[96:97], v[128:129], v[104:105]
	v_cvt_pk_bf16_f32 v96, v100, v101
	v_cvt_pk_bf16_f32 v97, v102, v103
	s_nop 0
	v_cvt_pk_bf16_f32 v98, v98, v99
	v_cvt_pk_bf16_f32 v99, v106, v107
	global_store_dwordx4 v199, v[96:99], s[6:7]
	s_nop 1
	v_lshlrev_b32_e32 v96, 16, v174
	v_and_b32_e32 v97, 0xffff0000, v174
	v_lshlrev_b32_e32 v98, 16, v175
	v_and_b32_e32 v99, 0xffff0000, v175
	v_pk_fma_f32 v[94:95], v[94:95], v[134:135], v[98:99]
	v_pk_fma_f32 v[92:93], v[92:93], v[132:133], v[96:97]
	v_lshlrev_b32_e32 v96, 16, v176
	v_and_b32_e32 v97, 0xffff0000, v176
	v_lshlrev_b32_e32 v98, 16, v177
	v_and_b32_e32 v99, 0xffff0000, v177
;     __device__ __forceinline__ void operator()(const f32x4 (&acc)[2][2][4][2], const Unit& u, int wr, int wc, int fr, int fq) const {
;     ...
;         for (int bj = 0; bj < 2; ++bj) { const int cb = c0 + bj * HALF;
;             const f32x4 g0 = ldb<f32x4>(gate, (unsigned)((b * NMOD + cb) * 4)), g1 = ldb<f32x4>(gate, (unsigned)((b * NMOD + cb + 4) * 4));
;             f32x4 m0 = (f32x4){0.f, 0.f, 0.f, 0.f}, m1 = m0; if (gm) { m0 = ldb<f32x4>(gm, (unsigned)((b * DM + cb) * 4)); m1 = ldb<f32x4>(gm, (unsigned)((b * DM + cb + 4) * 4)); }
;             if (XF32) {
; #pragma unroll
;                 for (int ai = 0; ai < 2; ++ai) {
;                     f32x4 xv[4][2];
; #pragma unroll
;                     for (int m = 0; m < 4; ++m) { const unsigned off = (unsigned)((PG8_ROW(u, ai, m) * DM + cb) * 4); xv[m][0] = ldb<f32x4>(xin, off); xv[m][1] = ldb<f32x4>(xin, off + 16); }
;                     PG8_FENCE();
; #pragma unroll
;                     for (int m = 0; m < 4; ++m) { const unsigned off = (unsigned)((PG8_ROW(u, ai, m) * DM + cb) * 2), offx = (unsigned)(PG8_ROW(u, ai, m) * (DM * 4) + DM * 2 + cb * 2);
;                         const f32x4 x0 = xv[m][0] + g0 * (acc[ai][bj][m][0] * rs[ai][m]), x1 = xv[m][1] + g1 * (acc[ai][bj][m][1] * rs[ai][m]);
;                         stb(xout, offx, pack8(x0, x1));
;                         if (gm) { ss[ai][m] += hsq4(x0) + hsq4(x1); stb(A, off, pack8(x0 * m0, x1 * m1)); } }
;                     PG8_FENCE(); }
;             } else {
;                 u32x4 xw[2][4];
; #pragma unroll
;                 for (int ai = 0; ai < 2; ++ai)
; #pragma unroll
;                     for (int m = 0; m < 4; ++m) xw[ai][m] = ldb<u32x4>(xin, (unsigned)(PG8_ROW(u, ai, m) * (DM * 4) + DM * 2 + cb * 2));
;                 PG8_FENCE();
; #pragma unroll
;                 for (int ai = 0; ai < 2; ++ai)
; #pragma unroll
;                     for (int m = 0; m < 4; ++m) { const unsigned off = (unsigned)((PG8_ROW(u, ai, m) * DM + cb) * 2), offx = (unsigned)(PG8_ROW(u, ai, m) * (DM * 4) + DM * 2 + cb * 2);
;                         const f32x4 x0 = bf_lo4(xw[ai][m]) + g0 * (acc[ai][bj][m][0] * rs[ai][m]), x1 = bf_hi4(xw[ai][m]) + g1 * (acc[ai][bj][m][1] * rs[ai][m]);
;                         stb(xout, offx, pack8(x0, x1));
;                         if (gm) { ss[ai][m] += hsq4(x0) + hsq4(x1); stb(A, off, pack8(x0 * m0, x1 * m1)); } }
	v_pk_fma_f32 v[98:99], v[90:91], v[130:131], v[98:99]
	v_pk_fma_f32 v[90:91], v[88:89], v[128:129], v[96:97]
	v_cvt_pk_bf16_f32 v88, v92, v93
	v_cvt_pk_bf16_f32 v89, v94, v95
	s_nop 0
	v_cvt_pk_bf16_f32 v90, v90, v91
	v_cvt_pk_bf16_f32 v91, v98, v99
	global_store_dwordx4 v201, v[88:91], s[6:7]
	s_nop 1
	v_lshlrev_b32_e32 v88, 16, v144
	v_and_b32_e32 v89, 0xffff0000, v144
	v_lshlrev_b32_e32 v90, 16, v145
	v_and_b32_e32 v91, 0xffff0000, v145
	v_pk_fma_f32 v[86:87], v[86:87], v[134:135], v[90:91]
	v_pk_fma_f32 v[84:85], v[84:85], v[132:133], v[88:89]
	v_lshlrev_b32_e32 v88, 16, v146
	v_and_b32_e32 v89, 0xffff0000, v146
	v_lshlrev_b32_e32 v90, 16, v147
	v_and_b32_e32 v91, 0xffff0000, v147
	v_pk_fma_f32 v[90:91], v[82:83], v[130:131], v[90:91]
	v_pk_fma_f32 v[82:83], v[80:81], v[128:129], v[88:89]
	v_cvt_pk_bf16_f32 v80, v84, v85
	v_cvt_pk_bf16_f32 v81, v86, v87
	s_nop 0
	v_cvt_pk_bf16_f32 v82, v82, v83
	v_cvt_pk_bf16_f32 v83, v90, v91
	global_store_dwordx4 v205, v[80:83], s[6:7]
	s_nop 1
	v_lshlrev_b32_e32 v80, 16, v140
	v_and_b32_e32 v81, 0xffff0000, v140
	v_lshlrev_b32_e32 v82, 16, v141
	v_and_b32_e32 v83, 0xffff0000, v141
	v_pk_fma_f32 v[78:79], v[78:79], v[134:135], v[82:83]
	v_pk_fma_f32 v[76:77], v[76:77], v[132:133], v[80:81]
	v_lshlrev_b32_e32 v80, 16, v142
	v_and_b32_e32 v81, 0xffff0000, v142
	v_lshlrev_b32_e32 v82, 16, v143
	v_and_b32_e32 v83, 0xffff0000, v143
	v_pk_fma_f32 v[82:83], v[74:75], v[130:131], v[82:83]
	v_pk_fma_f32 v[74:75], v[72:73], v[128:129], v[80:81]
	v_cvt_pk_bf16_f32 v72, v76, v77
	v_cvt_pk_bf16_f32 v73, v78, v79
	s_nop 0
	v_cvt_pk_bf16_f32 v74, v74, v75
	v_cvt_pk_bf16_f32 v75, v82, v83
	global_store_dwordx4 v206, v[72:75], s[6:7]
	s_nop 1
	v_lshlrev_b32_e32 v72, 16, v136
	v_and_b32_e32 v73, 0xffff0000, v136
	v_lshlrev_b32_e32 v74, 16, v137
	v_and_b32_e32 v75, 0xffff0000, v137
	v_pk_fma_f32 v[70:71], v[70:71], v[134:135], v[74:75]
	v_pk_fma_f32 v[68:69], v[68:69], v[132:133], v[72:73]
	v_lshlrev_b32_e32 v72, 16, v138
	v_and_b32_e32 v73, 0xffff0000, v138
	v_lshlrev_b32_e32 v74, 16, v139
	v_and_b32_e32 v75, 0xffff0000, v139
	v_pk_fma_f32 v[74:75], v[66:67], v[130:131], v[74:75]
	v_pk_fma_f32 v[66:67], v[64:65], v[128:129], v[72:73]
	v_cvt_pk_bf16_f32 v64, v68, v69
	v_cvt_pk_bf16_f32 v65, v70, v71
	s_nop 0
	v_cvt_pk_bf16_f32 v66, v66, v67
	v_cvt_pk_bf16_f32 v67, v74, v75
	global_store_dwordx4 v207, v[64:67], s[6:7]
	s_nop 1
	v_add_u32_e32 v64, 0x80, v192
	v_lshl_add_u32 v72, v64, 1, v157
	v_add_u32_e32 v106, v72, v193
	v_add_lshl_u32 v64, v64, s11, 2
	v_or_b32_e32 v64, 16, v64
	v_add_u32_e32 v107, v72, v194
	v_add_u32_e32 v108, v72, v196
	v_add_u32_e32 v109, v72, v198
	v_add_u32_e32 v110, v72, v200
	v_add_u32_e32 v111, v72, v202
	v_add_u32_e32 v112, v72, v203
	v_add_u32_e32 v113, v72, v204
	s_waitcnt vmcnt(8)
;     __device__ __forceinline__ void operator()(const f32x4 (&acc)[2][2][4][2], const Unit& u, int wr, int wc, int fr, int fq) const {
;     ...
;         for (int bj = 0; bj < 2; ++bj) { const int cb = c0 + bj * HALF;
;             const f32x4 g0 = ldb<f32x4>(gate, (unsigned)((b * NMOD + cb) * 4)), g1 = ldb<f32x4>(gate, (unsigned)((b * NMOD + cb + 4) * 4));
;             f32x4 m0 = (f32x4){0.f, 0.f, 0.f, 0.f}, m1 = m0; if (gm) { m0 = ldb<f32x4>(gm, (unsigned)((b * DM + cb) * 4)); m1 = ldb<f32x4>(gm, (unsigned)((b * DM + cb + 4) * 4)); }
;             if (XF32) {
; #pragma unroll
;                 for (int ai = 0; ai < 2; ++ai) {
;                     f32x4 xv[4][2];
; #pragma unroll
;                     for (int m = 0; m < 4; ++m) { const unsigned off = (unsigned)((PG8_ROW(u, ai, m) * DM + cb) * 4); xv[m][0] = ldb<f32x4>(xin, off); xv[m][1] = ldb<f32x4>(xin, off + 16); }
;                     PG8_FENCE();
; #pragma unroll
;                     for (int m = 0; m < 4; ++m) { const unsigned off = (unsigned)((PG8_ROW(u, ai, m) * DM + cb) * 2), offx = (unsigned)(PG8_ROW(u, ai, m) * (DM * 4) + DM * 2 + cb * 2);
;                         const f32x4 x0 = xv[m][0] + g0 * (acc[ai][bj][m][0] * rs[ai][m]), x1 = xv[m][1] + g1 * (acc[ai][bj][m][1] * rs[ai][m]);
;                         stb(xout, offx, pack8(x0, x1));
;                         if (gm) { ss[ai][m] += hsq4(x0) + hsq4(x1); stb(A, off, pack8(x0 * m0, x1 * m1)); } }
;                     PG8_FENCE(); }
;             } else {
;                 u32x4 xw[2][4];
; #pragma unroll
;                 for (int ai = 0; ai < 2; ++ai)
; #pragma unroll
;                     for (int m = 0; m < 4; ++m) xw[ai][m] = ldb<u32x4>(xin, (unsigned)(PG8_ROW(u, ai, m) * (DM * 4) + DM * 2 + cb * 2));
;                 PG8_FENCE();
; #pragma unroll
;                 for (int ai = 0; ai < 2; ++ai)
; #pragma unroll
;                     for (int m = 0; m < 4; ++m) { const unsigned off = (unsigned)((PG8_ROW(u, ai, m) * DM + cb) * 2), offx = (unsigned)(PG8_ROW(u, ai, m) * (DM * 4) + DM * 2 + cb * 2);
;                         const f32x4 x0 = bf_lo4(xw[ai][m]) + g0 * (acc[ai][bj][m][0] * rs[ai][m]), x1 = bf_hi4(xw[ai][m]) + g1 * (acc[ai][bj][m][1] * rs[ai][m]);
;                         stb(xout, offx, pack8(x0, x1));
;                         if (gm) { ss[ai][m] += hsq4(x0) + hsq4(x1); stb(A, off, pack8(x0 * m0, x1 * m1)); } }
	v_mov_b32_e32 v80, v212
	v_mov_b32_e32 v81, v213
	v_mov_b32_e32 v82, v214
	v_mov_b32_e32 v83, v215
	v_mov_b32_e32 v68, v216
	v_mov_b32_e32 v69, v217
	v_mov_b32_e32 v70, v218
	v_mov_b32_e32 v71, v219
	v_mov_b32_e32 v64, v220
	v_mov_b32_e32 v65, v221
	v_mov_b32_e32 v66, v222
	v_mov_b32_e32 v67, v223
	v_mov_b32_e32 v84, v224
	v_mov_b32_e32 v85, v225
	v_mov_b32_e32 v86, v226
	v_mov_b32_e32 v87, v227
	v_mov_b32_e32 v88, v228
	v_mov_b32_e32 v89, v229
	v_mov_b32_e32 v90, v230
	v_mov_b32_e32 v91, v231
	v_mov_b32_e32 v92, v232
	v_mov_b32_e32 v93, v233
	v_mov_b32_e32 v94, v234
	v_mov_b32_e32 v95, v235
	v_mov_b32_e32 v96, v240
	v_mov_b32_e32 v97, v241
	v_mov_b32_e32 v98, v242
	v_mov_b32_e32 v99, v243
	v_mov_b32_e32 v100, v244
	v_mov_b32_e32 v101, v245
	v_mov_b32_e32 v102, v246
	v_mov_b32_e32 v103, v247
	v_mov_b32_e32 v76, v248
	v_mov_b32_e32 v77, v249
	v_mov_b32_e32 v78, v250
	v_mov_b32_e32 v79, v251
	v_mov_b32_e32 v72, v252
	v_mov_b32_e32 v73, v253
	v_mov_b32_e32 v74, v254
	v_mov_b32_e32 v75, v255
	v_lshlrev_b32_e32 v104, 16, v80
	v_and_b32_e32 v105, 0xffff0000, v80
	v_lshlrev_b32_e32 v80, 16, v81
	v_and_b32_e32 v81, 0xffff0000, v81
	s_nop 0
	v_pk_fma_f32 v[62:63], v[62:63], v[70:71], v[80:81]
	v_lshlrev_b32_e32 v80, 16, v82
	v_and_b32_e32 v81, 0xffff0000, v82
	v_lshlrev_b32_e32 v82, 16, v83
	v_and_b32_e32 v83, 0xffff0000, v83
	s_nop 0
	v_pk_fma_f32 v[82:83], v[58:59], v[66:67], v[82:83]
	v_pk_fma_f32 v[58:59], v[56:57], v[64:65], v[80:81]
	v_pk_fma_f32 v[60:61], v[60:61], v[68:69], v[104:105]
	s_nop 0
	v_cvt_pk_bf16_f32 v56, v60, v61
	v_cvt_pk_bf16_f32 v57, v62, v63
	v_cvt_pk_bf16_f32 v58, v58, v59
	v_cvt_pk_bf16_f32 v59, v82, v83
	global_store_dwordx4 v106, v[56:59], s[6:7]
	s_nop 0
	s_nop 0
	v_lshlrev_b32_e32 v56, 16, v84
	v_and_b32_e32 v57, 0xffff0000, v84
	v_lshlrev_b32_e32 v58, 16, v85
	v_and_b32_e32 v59, 0xffff0000, v85
	v_pk_fma_f32 v[54:55], v[54:55], v[70:71], v[58:59]
	v_pk_fma_f32 v[52:53], v[52:53], v[68:69], v[56:57]
	v_lshlrev_b32_e32 v56, 16, v86
	v_and_b32_e32 v57, 0xffff0000, v86
	v_lshlrev_b32_e32 v58, 16, v87
	v_and_b32_e32 v59, 0xffff0000, v87
	v_pk_fma_f32 v[58:59], v[50:51], v[66:67], v[58:59]
	v_pk_fma_f32 v[50:51], v[48:49], v[64:65], v[56:57]
	v_cvt_pk_bf16_f32 v48, v52, v53
	v_cvt_pk_bf16_f32 v49, v54, v55
	s_nop 0
	v_cvt_pk_bf16_f32 v50, v50, v51
	v_cvt_pk_bf16_f32 v51, v58, v59
	global_store_dwordx4 v107, v[48:51], s[6:7]
	s_nop 0
	s_nop 0
	v_lshlrev_b32_e32 v48, 16, v88
	v_and_b32_e32 v49, 0xffff0000, v88
	v_lshlrev_b32_e32 v50, 16, v89
	v_and_b32_e32 v51, 0xffff0000, v89
	v_pk_fma_f32 v[46:47], v[46:47], v[70:71], v[50:51]
	v_pk_fma_f32 v[44:45], v[44:45], v[68:69], v[48:49]
	v_lshlrev_b32_e32 v48, 16, v90
	v_and_b32_e32 v49, 0xffff0000, v90
	v_lshlrev_b32_e32 v50, 16, v91
	v_and_b32_e32 v51, 0xffff0000, v91
	v_pk_fma_f32 v[50:51], v[42:43], v[66:67], v[50:51]
	v_pk_fma_f32 v[42:43], v[40:41], v[64:65], v[48:49]
	v_cvt_pk_bf16_f32 v40, v44, v45
	v_cvt_pk_bf16_f32 v41, v46, v47
	s_nop 0
	v_cvt_pk_bf16_f32 v42, v42, v43
	v_cvt_pk_bf16_f32 v43, v50, v51
	global_store_dwordx4 v108, v[40:43], s[6:7]
	s_nop 0
	s_nop 0
	v_lshlrev_b32_e32 v40, 16, v92
	v_and_b32_e32 v41, 0xffff0000, v92
	v_lshlrev_b32_e32 v42, 16, v93
	v_and_b32_e32 v43, 0xffff0000, v93
	v_pk_fma_f32 v[38:39], v[38:39], v[70:71], v[42:43]
	v_pk_fma_f32 v[36:37], v[36:37], v[68:69], v[40:41]
	v_lshlrev_b32_e32 v40, 16, v94
	v_and_b32_e32 v41, 0xffff0000, v94
	v_lshlrev_b32_e32 v42, 16, v95
	v_and_b32_e32 v43, 0xffff0000, v95
	v_pk_fma_f32 v[42:43], v[34:35], v[66:67], v[42:43]
	v_pk_fma_f32 v[34:35], v[32:33], v[64:65], v[40:41]
	v_cvt_pk_bf16_f32 v32, v36, v37
	v_cvt_pk_bf16_f32 v33, v38, v39
	s_nop 0
	v_cvt_pk_bf16_f32 v34, v34, v35
	v_cvt_pk_bf16_f32 v35, v42, v43
	global_store_dwordx4 v109, v[32:35], s[6:7]
	s_nop 0
	s_nop 0
	v_lshlrev_b32_e32 v32, 16, v96
	v_and_b32_e32 v33, 0xffff0000, v96
	v_lshlrev_b32_e32 v34, 16, v97
	v_and_b32_e32 v35, 0xffff0000, v97
	v_pk_fma_f32 v[30:31], v[30:31], v[70:71], v[34:35]
	v_pk_fma_f32 v[28:29], v[28:29], v[68:69], v[32:33]
	v_lshlrev_b32_e32 v32, 16, v98
	v_and_b32_e32 v33, 0xffff0000, v98
	v_lshlrev_b32_e32 v34, 16, v99
	v_and_b32_e32 v35, 0xffff0000, v99
	v_pk_fma_f32 v[34:35], v[26:27], v[66:67], v[34:35]
	v_pk_fma_f32 v[26:27], v[24:25], v[64:65], v[32:33]
	v_cvt_pk_bf16_f32 v24, v28, v29
	v_cvt_pk_bf16_f32 v25, v30, v31
	s_nop 0
	v_cvt_pk_bf16_f32 v26, v26, v27
	v_cvt_pk_bf16_f32 v27, v34, v35
	global_store_dwordx4 v110, v[24:27], s[6:7]
	s_nop 0
	s_nop 0
	v_lshlrev_b32_e32 v24, 16, v100
	v_and_b32_e32 v25, 0xffff0000, v100
	v_lshlrev_b32_e32 v26, 16, v101
	v_and_b32_e32 v27, 0xffff0000, v101
	v_pk_fma_f32 v[22:23], v[22:23], v[70:71], v[26:27]
	v_pk_fma_f32 v[20:21], v[20:21], v[68:69], v[24:25]
	v_lshlrev_b32_e32 v24, 16, v102
	v_and_b32_e32 v25, 0xffff0000, v102
	v_lshlrev_b32_e32 v26, 16, v103
	v_and_b32_e32 v27, 0xffff0000, v103
	v_pk_fma_f32 v[26:27], v[18:19], v[66:67], v[26:27]
	v_pk_fma_f32 v[18:19], v[16:17], v[64:65], v[24:25]
	v_cvt_pk_bf16_f32 v16, v20, v21
	v_cvt_pk_bf16_f32 v17, v22, v23
	s_nop 0
	v_cvt_pk_bf16_f32 v18, v18, v19
	v_cvt_pk_bf16_f32 v19, v26, v27
	global_store_dwordx4 v111, v[16:19], s[6:7]
	s_nop 0
	s_nop 0
	v_lshlrev_b32_e32 v16, 16, v76
	v_and_b32_e32 v17, 0xffff0000, v76
	v_lshlrev_b32_e32 v18, 16, v77
	v_and_b32_e32 v19, 0xffff0000, v77
	v_pk_fma_f32 v[14:15], v[14:15], v[70:71], v[18:19]
	v_pk_fma_f32 v[12:13], v[12:13], v[68:69], v[16:17]
	v_lshlrev_b32_e32 v16, 16, v78
	v_and_b32_e32 v17, 0xffff0000, v78
	v_lshlrev_b32_e32 v18, 16, v79
	v_and_b32_e32 v19, 0xffff0000, v79
	v_pk_fma_f32 v[18:19], v[10:11], v[66:67], v[18:19]
	v_pk_fma_f32 v[10:11], v[8:9], v[64:65], v[16:17]
	v_cvt_pk_bf16_f32 v8, v12, v13
	v_cvt_pk_bf16_f32 v9, v14, v15
	s_nop 0
	v_cvt_pk_bf16_f32 v10, v10, v11
	v_cvt_pk_bf16_f32 v11, v18, v19
	global_store_dwordx4 v112, v[8:11], s[6:7]
	s_nop 0
	s_nop 0
	v_lshlrev_b32_e32 v8, 16, v72
	v_and_b32_e32 v9, 0xffff0000, v72
	v_lshlrev_b32_e32 v10, 16, v73
	v_and_b32_e32 v11, 0xffff0000, v73
	v_pk_fma_f32 v[6:7], v[6:7], v[70:71], v[10:11]
	v_pk_fma_f32 v[4:5], v[4:5], v[68:69], v[8:9]
	v_lshlrev_b32_e32 v8, 16, v74
	v_and_b32_e32 v9, 0xffff0000, v74
	v_lshlrev_b32_e32 v10, 16, v75
	v_and_b32_e32 v11, 0xffff0000, v75
	v_pk_fma_f32 v[10:11], v[2:3], v[66:67], v[10:11]
	v_pk_fma_f32 v[2:3], v[0:1], v[64:65], v[8:9]
	v_cvt_pk_bf16_f32 v0, v4, v5
	v_cvt_pk_bf16_f32 v1, v6, v7
	s_nop 0
	v_cvt_pk_bf16_f32 v2, v2, v3
	v_cvt_pk_bf16_f32 v3, v10, v11
	global_store_dwordx4 v113, v[0:3], s[6:7]
	s_cbranch_vccnz .LBB13_2159
	s_andn2_b64 vcc, exec, s[2:3]
	s_cbranch_vccnz .LBB13_2158
	s_barrier
	s_branch .LBB13_2158
